# k21: k20 + attention epilogue gate rows prefetched in the unit prologue into spare registers (no cold load inside the epilogue)
# baseline (speedup 1.0000x reference)
; #define LAS __attribute__((address_space(3)))
; #define ATT_GLD16(dst, ptr) asm volatile("global_load_dwordx4 %0, %1, off" : "=&v"(dst) : "v"(ptr) : "memory")
; __device__ __forceinline__ void attn_unit(const UnitDesc& u, LAS unsigned char* shm, float qkmax, float thresh) {
;     ...
;     const int NT = (u.q0 + u.nq) >> 6, nband = u.nq >> 6;
;     const bool active = wid * 32 < u.nq;
;     LAS float* wsf = (LAS float*)(shm + LDS_WS) + wid * 128;
;     const bf16_t* ksrc = u.K + (size_t)lane * 512 + wid * 8;
;     const bf16_t* vsrc = u.V + (size_t)(16 * (wid & 3) + (lane >> 2)) * 512 + (wid >> 2) * 32 + (lane & 3) * 8;
;     const float* lsrc = u.LF + (size_t)lane * 8;
;     LAS unsigned char* kdst = shm + LDS_K + wid * 1024 + lane * 16;
;     LAS unsigned char* vdst = shm + LDS_V + wid * 1024 + lane * 16;
;     const int vb0 = (int)(unsigned)(uintptr_t)(shm + LDS_V) + ((lane >> 4) & 1) * 32 + (lane & 3) * 8 + (4 * hi + ((lane & 15) >> 2)) * 64;
;     const LAS unsigned char* kb = shm + LDS_K + hi * 1024 + r32 * 16;
;     ...
;     u32x4 kreg = *(const u32x4*)(ksrc + (size_t)(NT - 1) * 64 * 512), vreg = *(const u32x4*)(vsrc + (size_t)(NT - 1) * 64 * 512);
;     float lfb[4];
; #pragma unroll
;     for (int jb = 0; jb < 4; ++jb) { const int tile = NT - 1 - jb; lfb[jb] = lsrc[(size_t)(tile > 0 ? tile : 0) * 64 * 8]; }
;     u32x4 kA, vA, kB, vB, kC, vC;
;     { const int t2 = NT >= 2 ? NT - 2 : 0, t3 = NT >= 3 ? NT - 3 : 0, t4 = NT >= 4 ? NT - 4 : 0;
;       ATT_GLD16(kA, ksrc + (size_t)t2 * 64 * 512); ATT_GLD16(vA, vsrc + (size_t)t2 * 64 * 512);
;       ATT_GLD16(kB, ksrc + (size_t)t3 * 64 * 512); ATT_GLD16(vB, vsrc + (size_t)t3 * 64 * 512);
;       ATT_GLD16(kC, ksrc + (size_t)t4 * 64 * 512); ATT_GLD16(vC, vsrc + (size_t)t4 * 64 * 512); }
;     bf16x8 qr[4];
; #pragma unroll
;     for (int d0 = 0; d0 < 4; ++d0) qr[d0] = (bf16x8){0, 0, 0, 0, 0, 0, 0, 0};
;     if (active) { const bf16_t* Qw = u.Q + (size_t)(wid * 32 + r32) * 512;
; #pragma unroll
;         for (int d0 = 0; d0 < 4; ++d0) qr[d0] = *(const bf16x8*)(Qw + d0 * 16 + hi * 8); }
;     ...
;         u32x4 zv4[4];
; #pragma unroll
;         for (int i = 0; i < 4; ++i) zv4[i] = *(const u32x4*)(u.Zg + (size_t)(wid * 32 + i * 8 + (lane >> 3)) * 512 + (lane & 7) * 8);
.LBB0_731:
	s_lshl_b64 s[48:49], s[28:29], 2
	v_mov_b32_e32 v12, v208
	s_add_u32 s12, s12, s48
	s_addc_u32 s13, s13, s49
	v_and_b32_e32 v137, 63, v12
	v_readfirstlane_b32 s68, v12
	s_ashr_i32 s52, s68, 6
	v_lshlrev_b32_e32 v0, 10, v137
	v_lshl_add_u64 v[2:3], s[10:11], 0, v[0:1]
	s_lshl_b32 s10, s52, 3
	s_ashr_i32 s11, s10, 31
	v_lshl_add_u64 v[106:107], s[10:11], 1, v[2:3]
	s_lshl_b32 s10, s52, 4
	v_bfe_u32 v0, v12, 2, 4
	v_and_or_b32 v0, s10, 48, v0
	v_lshlrev_b32_e32 v0, 10, v0
	s_add_i32 s28, s53, s66
	v_lshl_add_u64 v[2:3], s[8:9], 0, v[0:1]
	s_ashr_i32 s8, s68, 3
	s_ashr_i32 s67, s28, 6
	s_andn2_b32 s8, s8, 31
	v_lshlrev_b32_e32 v138, 3, v12
	s_ashr_i32 s9, s8, 31
	v_and_b32_e32 v13, 24, v138
	s_add_i32 s48, s67, -1
	v_lshl_add_u64 v[2:3], s[8:9], 1, v[2:3]
	v_lshlrev_b32_e32 v0, 1, v13
	s_ashr_i32 s49, s48, 31
	v_lshl_add_u64 v[108:109], v[2:3], 0, v[0:1]
	v_lshlrev_b32_e32 v0, 5, v137
	s_lshl_b64 s[8:9], s[48:49], 16
	s_max_i32 s28, s48, 0
	v_lshl_add_u64 v[110:111], s[12:13], 0, v[0:1]
	v_lshl_add_u64 v[2:3], v[106:107], 0, s[8:9]
	v_lshl_add_u64 v[6:7], v[108:109], 0, s[8:9]
	s_lshl_b64 s[8:9], s[28:29], 11
	v_lshl_add_u64 v[10:11], v[110:111], 0, s[8:9]
	s_max_i32 s8, s67, 2
	s_add_i32 s28, s8, -2
	s_lshl_b64 s[8:9], s[28:29], 11
	v_lshl_add_u64 v[16:17], v[110:111], 0, s[8:9]
	s_max_i32 s8, s67, 3
	s_add_i32 s8, s8, -3
	s_mov_b32 s9, s29
	s_lshl_b64 s[10:11], s[8:9], 11
	v_lshl_add_u64 v[18:19], v[110:111], 0, s[10:11]
	s_max_i32 s10, s67, 4
	s_add_i32 s10, s10, -4
	s_mov_b32 s11, s29
	s_lshl_b64 s[12:13], s[10:11], 11
	global_load_dwordx4 v[2:5], v[2:3], off
	v_lshl_add_u64 v[20:21], v[110:111], 0, s[12:13]
	global_load_dwordx4 v[6:9], v[6:7], off
	s_nop 0
	global_load_dword v14, v[10:11], off
	global_load_dword v140, v[16:17], off
	global_load_dword v141, v[18:19], off
	global_load_dword v139, v[20:21], off
	s_lshl_b32 s49, s52, 5
	s_cmp_lt_i32 s49, s53
	s_cselect_b64 s[58:59], -1, 0
	s_cmp_ge_i32 s49, s53
	s_cselect_b64 s[60:61], -1, 0
	s_lshl_b64 s[12:13], s[28:29], 16
	v_lshl_add_u64 v[10:11], v[106:107], 0, s[12:13]
	global_load_dwordx4 v[66:69], v[10:11], off
	v_lshl_add_u64 v[10:11], v[108:109], 0, s[12:13]
	global_load_dwordx4 v[74:77], v[10:11], off
	s_lshl_b64 s[8:9], s[8:9], 16
	v_lshl_add_u64 v[10:11], v[106:107], 0, s[8:9]
	global_load_dwordx4 v[70:73], v[10:11], off
	v_lshl_add_u64 v[10:11], v[108:109], 0, s[8:9]
	global_load_dwordx4 v[82:85], v[10:11], off
	s_lshl_b64 s[8:9], s[10:11], 16
	v_lshl_add_u64 v[10:11], v[106:107], 0, s[8:9]
	global_load_dwordx4 v[78:81], v[10:11], off
	v_lshl_add_u64 v[10:11], v[108:109], 0, s[8:9]
	global_load_dwordx4 v[86:89], v[10:11], off
	v_and_b32_e32 v135, 31, v12
	v_bfe_u32 v136, v12, 5, 1
	s_and_b64 vcc, exec, s[60:61]
	v_or_b32_e32 v10, s49, v135
	s_cbranch_vccnz .LBB0_733
	v_ashrrev_i32_e32 v11, 31, v10
	v_lshlrev_b64 v[16:17], 10, v[10:11]
	v_lshl_add_u64 v[16:17], s[6:7], 0, v[16:17]
	v_lshlrev_b32_e32 v0, 4, v136
	v_lshl_add_u64 v[16:17], v[16:17], 0, v[0:1]
	global_load_dwordx4 v[94:97], v[16:17], off
	global_load_dwordx4 v[98:101], v[16:17], off offset:32
	global_load_dwordx4 v[102:105], v[16:17], off offset:64
	global_load_dwordx4 v[90:93], v[16:17], off offset:96
	s_lshl_b64 s[82:83], s[44:45], 1
	s_add_u32 s82, s24, s82
	s_addc_u32 s83, s25, s83
	s_lshl_b64 s[100:101], s[46:47], 1
	s_add_u32 s82, s82, s100
	s_addc_u32 s83, s83, s101
	v_lshrrev_b32_e32 v188, 3, v137
	v_or_b32_e32 v188, s49, v188
	v_and_b32_e32 v189, 56, v138
	v_lshlrev_b32_e32 v189, 1, v189
	v_lshl_add_u32 v188, v188, 10, v189
	v_add_u32_e32 v189, 0x2000, v188
	v_add_u32_e32 v190, 0x4000, v188
	v_add_u32_e32 v191, 0x6000, v188
	global_load_dwordx4 v[234:237], v188, s[82:83]
	global_load_dwordx4 v[238:241], v189, s[82:83]
	global_load_dwordx4 v[242:245], v190, s[82:83]
	global_load_dwordx4 v[246:249], v191, s[82:83]
	s_branch .LBB0_734

; #define LAS __attribute__((address_space(3)))
; __device__ __forceinline__ void attn_unit(const UnitDesc& u, LAS unsigned char* shm, float qkmax, float thresh) {
;     ...
;     asm volatile("s_waitcnt vmcnt(0)" : "+v"(kA), "+v"(vA), "+v"(kB), "+v"(vB), "+v"(kC), "+v"(vC), "+v"(lA), "+v"(lB), "+v"(lC) :: "memory");
;     if (active) {
;         u32x4 zv4[4];
; #pragma unroll
;         for (int i = 0; i < 4; ++i) zv4[i] = *(const u32x4*)(u.Zg + (size_t)(wid * 32 + i * 8 + (lane >> 3)) * 512 + (lane & 7) * 8);
;         { auto rr = __builtin_amdgcn_permlane32_swap(__float_as_uint(l_reg), __float_as_uint(l_reg), false, false); l_reg = __uint_as_float(rr[0]) + __uint_as_float(rr[1]); }
;         LAS float* lx = (LAS float*)(shm + LDS_LX) + wid * 32;
;         if (hi == 0) lx[r32] = l_reg;
.LBB0_829:
	s_or_b64 exec, exec, s[62:63]
	s_waitcnt vmcnt(0)
	s_and_b64 vcc, exec, s[12:13]
	s_cbranch_vccnz .LBB0_719
	s_nop 7
	s_nop 7
	v_mov_b64_e32 v[34:35], v[2:3]
	v_mov_b64_e32 v[36:37], v[4:5]
	v_mov_b64_e32 v[38:39], v[6:7]
	v_mov_b64_e32 v[40:41], v[8:9]
	v_mov_b64_e32 v[42:43], v[10:11]
	v_mov_b64_e32 v[44:45], v[12:13]
	v_mov_b64_e32 v[46:47], v[14:15]
	v_mov_b64_e32 v[48:49], v[16:17]
	v_mov_b64_e32 v[50:51], v[18:19]
	v_mov_b64_e32 v[52:53], v[20:21]
	v_mov_b64_e32 v[54:55], v[22:23]
	v_mov_b64_e32 v[56:57], v[24:25]
	v_mov_b64_e32 v[58:59], v[26:27]
	v_mov_b64_e32 v[60:61], v[28:29]
	v_mov_b64_e32 v[62:63], v[30:31]
	v_mov_b64_e32 v[64:65], v[32:33]
	s_lshl_b64 s[6:7], s[44:45], 1
	s_add_u32 s8, s24, s6
	v_lshrrev_b32_e32 v20, 3, v137
	s_addc_u32 s9, s25, s7
	s_lshl_b64 s[6:7], s[46:47], 1
	v_or_b32_e32 v18, s49, v20
	s_add_u32 s8, s8, s6
	v_and_b32_e32 v0, 56, v138
	v_or_b32_e32 v6, 8, v18
	s_addc_u32 s9, s9, s7
	v_lshlrev_b32_e32 v0, 1, v0
	v_ashrrev_i32_e32 v19, 31, v18
	v_ashrrev_i32_e32 v7, 31, v6
	v_lshl_add_u64 v[2:3], s[8:9], 0, v[0:1]
	v_lshlrev_b64 v[4:5], 10, v[18:19]
	v_lshlrev_b64 v[6:7], 10, v[6:7]
	v_lshl_add_u64 v[4:5], v[2:3], 0, v[4:5]
	v_lshl_add_u64 v[6:7], v[2:3], 0, v[6:7]
	v_or_b32_e32 v4, 16, v18
	v_or_b32_e32 v6, 24, v18
	v_ashrrev_i32_e32 v5, 31, v4
	v_ashrrev_i32_e32 v7, 31, v6
	v_lshlrev_b64 v[4:5], 10, v[4:5]
	v_lshlrev_b64 v[6:7], 10, v[6:7]
	v_lshl_add_u64 v[4:5], v[2:3], 0, v[4:5]
	v_lshl_add_u64 v[2:3], v[2:3], 0, v[6:7]
	s_nop 0
	v_mov_b64_e32 v[14:15], v[234:235]
	v_mov_b64_e32 v[16:17], v[236:237]
	v_mov_b64_e32 v[10:11], v[238:239]
	v_mov_b64_e32 v[12:13], v[240:241]
	v_mov_b64_e32 v[6:7], v[242:243]
	v_mov_b64_e32 v[8:9], v[244:245]
	v_mov_b64_e32 v[2:3], v[246:247]
	v_mov_b64_e32 v[4:5], v[248:249]
	v_mov_b32_e32 v21, v148
	s_lshl_b32 s8, s49, 2
	s_nop 0
	v_permlane32_swap_b32_e32 v148, v21
	s_add_i32 s10, s8, 0
	v_cmp_gt_u32_e32 vcc, 32, v137
	s_and_saveexec_b64 s[8:9], vcc
	s_cbranch_execz .LBB0_718
	v_add_f32_e32 v21, v148, v21
	v_lshl_add_u32 v22, v135, 2, s10
	ds_write_b32 v22, v21 offset:36864
	s_branch .LBB0_718
